# deferred layer-1 conversion: windows P2 480 / P3 512 / P5 320 tiles
# baseline (speedup 1.0000x reference)
.LBB0_17:
	s_mov_b32 s94, 0
	s_movk_i32 s93, 1280
	s_sub_i32 s92, 0xff, s2
	s_movk_i32 s90, 0x70
	s_cmpk_gt_i32 s92, 0x6f
	s_cbranch_scc1 .LBB0_52

.Lmy_cv_head:
	s_cmp_lg_u32 s94, 0
	s_cbranch_scc1 .Lmy_cv_map1
	s_movk_i32 s68, 1056
	s_cmpk_lt_i32 s92, 1056
	s_cselect_b32 s68, 704, s68
	s_cmpk_lt_i32 s92, 704
	s_cselect_b32 s68, 0, s68
	s_add_i32 s68, s68, s92
	s_branch .LBB0_21
.Lmy_cv_map1:
	s_movk_i32 s68, 1280
	s_cmpk_lt_i32 s92, 1056
	s_cselect_b32 s68, 1056, s68
	s_cmpk_lt_i32 s92, 704
	s_cselect_b32 s68, 704, s68
	s_add_i32 s68, s68, s92

.LBB0_232:
	s_waitcnt vmcnt(0)
	s_barrier
	s_cmp_lt_u32 s2, 176
	s_cbranch_scc1 .LBB0_233
	s_sub_i32 s92, s2, 176
	s_cmpk_ge_i32 s92, 480
	s_cbranch_scc1 .LBB0_233
	s_mov_b64 s[80:81], s[10:11]
	s_mov_b64 s[82:83], s[12:13]
	s_mov_b64 s[84:85], s[14:15]
	s_mov_b64 s[86:87], s[52:53]
	s_mov_b64 s[88:89], s[54:55]
	s_mov_b64 s[98:99], s[70:71]
	s_mov_b32 s94, 1
	s_movk_i32 s93, 480
	s_movk_i32 s90, 80
	s_branch .Lmy_cv_setup

.LBB0_371:
	s_waitcnt vmcnt(0)
	s_barrier
	s_cmp_lt_u32 s2, 128
	s_cbranch_scc1 .LBB0_372
	s_sub_i32 s92, s2, -352
	s_cmpk_ge_i32 s92, 992
	s_cbranch_scc1 .LBB0_372
	s_mov_b64 s[80:81], s[10:11]
	s_mov_b64 s[82:83], s[12:13]
	s_mov_b64 s[84:85], s[14:15]
	s_mov_b64 s[86:87], s[52:53]
	s_mov_b64 s[88:89], s[54:55]
	s_mov_b64 s[98:99], s[70:71]
	s_mov_b32 s94, 2
	s_movk_i32 s93, 992
	s_movk_i32 s90, 128
	s_branch .Lmy_cv_setup

.LBB0_560:
	s_waitcnt vmcnt(0)
	s_barrier
	s_cmp_lt_u32 s2, 32
	s_cbranch_scc1 .LBB0_561
	s_sub_i32 s92, s2, -960
	s_cmpk_ge_i32 s92, 1312
	s_cbranch_scc1 .LBB0_561
	s_mov_b64 s[80:81], s[10:11]
	s_mov_b64 s[82:83], s[12:13]
	s_mov_b64 s[84:85], s[14:15]
	s_mov_b64 s[86:87], s[52:53]
	s_mov_b64 s[88:89], s[54:55]
	s_mov_b64 s[98:99], s[70:71]
	s_mov_b32 s94, 3
	s_movk_i32 s93, 1312
	s_movk_i32 s90, 224
	s_branch .Lmy_cv_setup
